# combined: packed softmax subtracts plus removal of the 129 spare s_nop before v_rcp_f32, on top of v55
# baseline (speedup 1.0000x reference)
.LBB0_78:
	s_sext_i32_i16 s6, s6
	v_ashrrev_i32_e32 v0, 1, v211
	v_and_b32_e32 v0, 0xffffffc0, v0
	s_lshl_b32 s6, s6, 7
	v_add_u32_e32 v0, s8, v0
	s_waitcnt vmcnt(7)
	v_and_or_b32 v130, v211, 64, s6
	s_waitcnt vmcnt(6)
	v_and_or_b32 v134, v211, 31, v0
	v_ashrrev_i32_e32 v131, 31, v130
	v_lshrrev_b32_e32 v0, 1, v211
	v_lshl_add_u64 v[130:131], v[130:131], 1, s[0:1]
	v_and_b32_e32 v0, 16, v0
	v_lshl_add_u64 v[130:131], v[130:131], 0, v[0:1]
	v_mul_f32_e32 v0, 0xbfb8aa3b, v114
	v_exp_f32_e32 v136, v0
	v_mul_f32_e32 v0, 0xbfb8aa3b, v115
	v_exp_f32_e32 v137, v0
	s_movk_i32 s8, 0x1600
	v_mad_i64_i32 v[132:133], s[6:7], v134, s8, v[130:131]
	v_pk_add_f32 v[136:137], v[136:137], 1.0 op_sel_hi:[1,0]
	s_nop 2
	s_waitcnt vmcnt(5)
	s_nop 4
	v_rcp_f32_e32 v0, v137
	s_nop 0
	v_mul_f32_e32 v115, v115, v0
	v_rcp_f32_e32 v0, v136
	s_nop 0
	v_mul_f32_e32 v114, v114, v0
	v_mul_f32_e32 v0, 0xbfb8aa3b, v116
	v_pk_mul_f32 v[98:99], v[98:99], v[114:115]
	v_exp_f32_e32 v114, v0
	v_mul_f32_e32 v0, 0xbfb8aa3b, v117
	v_exp_f32_e32 v115, v0
	v_cvt_pk_bf16_f32 v98, v98, v99
	v_pk_add_f32 v[114:115], v[114:115], 1.0 op_sel_hi:[1,0]
	v_rcp_f32_e32 v0, v115
	s_nop 0
	v_mul_f32_e32 v115, v117, v0
	v_rcp_f32_e32 v0, v114
	s_nop 0
	v_mul_f32_e32 v114, v116, v0
	v_pk_mul_f32 v[100:101], v[100:101], v[114:115]
	v_mul_f32_e32 v0, 0xbfb8aa3b, v118
	v_cvt_pk_bf16_f32 v99, v100, v101
	v_exp_f32_e32 v100, v0
	v_mul_f32_e32 v0, 0xbfb8aa3b, v119
	v_exp_f32_e32 v101, v0
	s_nop 0
	v_pk_add_f32 v[100:101], v[100:101], 1.0 op_sel_hi:[1,0]
	v_rcp_f32_e32 v0, v101
	s_nop 0
	v_mul_f32_e32 v101, v119, v0
	v_rcp_f32_e32 v0, v100
	s_nop 0
	v_mul_f32_e32 v100, v118, v0
	v_mul_f32_e32 v0, 0xbfb8aa3b, v120
	v_pk_mul_f32 v[100:101], v[102:103], v[100:101]
	v_exp_f32_e32 v102, v0
	v_mul_f32_e32 v0, 0xbfb8aa3b, v121
	v_exp_f32_e32 v103, v0
	v_cvt_pk_bf16_f32 v100, v100, v101
	s_nop 1
	v_permlane32_swap_b32_e32 v98, v100
	v_pk_add_f32 v[102:103], v[102:103], 1.0 op_sel_hi:[1,0]
	v_rcp_f32_e32 v0, v103
	s_nop 0
	v_mul_f32_e32 v103, v121, v0
	v_rcp_f32_e32 v0, v102
	s_nop 0
	v_mul_f32_e32 v102, v120, v0
	v_pk_mul_f32 v[102:103], v[104:105], v[102:103]
	v_mul_f32_e32 v0, 0xbfb8aa3b, v122
	v_cvt_pk_bf16_f32 v101, v102, v103
	s_nop 1
	v_permlane32_swap_b32_e32 v99, v101
	global_store_dwordx4 v[132:133], v[98:101], off
	s_nop 1
	v_exp_f32_e32 v98, v0
	v_mul_f32_e32 v0, 0xbfb8aa3b, v123
	v_exp_f32_e32 v99, v0
	s_nop 0
	v_pk_add_f32 v[98:99], v[98:99], 1.0 op_sel_hi:[1,0]
	v_rcp_f32_e32 v0, v99
	s_nop 0
	v_mul_f32_e32 v99, v123, v0
	v_rcp_f32_e32 v0, v98
	s_nop 0
	v_mul_f32_e32 v98, v122, v0
	v_mul_f32_e32 v0, 0xbfb8aa3b, v124
	v_exp_f32_e32 v100, v0
	v_mul_f32_e32 v0, 0xbfb8aa3b, v125
	v_exp_f32_e32 v101, v0
	v_pk_mul_f32 v[98:99], v[106:107], v[98:99]
	v_pk_add_f32 v[100:101], v[100:101], 1.0 op_sel_hi:[1,0]
	s_nop 2
	v_cvt_pk_bf16_f32 v98, v98, v99
	v_rcp_f32_e32 v0, v101
	s_nop 0
	v_mul_f32_e32 v101, v125, v0
	v_rcp_f32_e32 v0, v100
	s_nop 0
	v_mul_f32_e32 v100, v124, v0
	v_pk_mul_f32 v[100:101], v[108:109], v[100:101]
	v_mul_f32_e32 v0, 0xbfb8aa3b, v126
	v_cvt_pk_bf16_f32 v99, v100, v101
	v_exp_f32_e32 v100, v0
	v_mul_f32_e32 v0, 0xbfb8aa3b, v127
	v_exp_f32_e32 v101, v0
	s_nop 0
	v_pk_add_f32 v[100:101], v[100:101], 1.0 op_sel_hi:[1,0]
	v_rcp_f32_e32 v0, v101
	s_nop 0
	v_mul_f32_e32 v101, v127, v0
	v_rcp_f32_e32 v0, v100
	s_nop 0
	v_mul_f32_e32 v100, v126, v0
	v_mul_f32_e32 v0, 0xbfb8aa3b, v128
	v_exp_f32_e32 v102, v0
	v_mul_f32_e32 v0, 0xbfb8aa3b, v129
	v_exp_f32_e32 v103, v0
	v_pk_mul_f32 v[100:101], v[110:111], v[100:101]
	v_pk_add_f32 v[102:103], v[102:103], 1.0 op_sel_hi:[1,0]
	s_nop 2
	v_cvt_pk_bf16_f32 v100, v100, v101
	s_nop 1
	v_permlane32_swap_b32_e32 v98, v100
	s_nop 4
	v_rcp_f32_e32 v0, v103
	s_nop 0
	v_mul_f32_e32 v103, v129, v0
	v_rcp_f32_e32 v0, v102
	s_nop 0
	v_mul_f32_e32 v102, v128, v0
	v_pk_mul_f32 v[102:103], v[112:113], v[102:103]
	v_mul_f32_e32 v0, 0xbfb8aa3b, v82
	v_cvt_pk_bf16_f32 v101, v102, v103
	s_nop 1
	v_permlane32_swap_b32_e32 v99, v101
	global_store_dwordx4 v[132:133], v[98:101], off offset:32
	s_nop 1
	v_exp_f32_e32 v98, v0
	v_mul_f32_e32 v0, 0xbfb8aa3b, v83
	v_exp_f32_e32 v99, v0
	s_nop 0
	v_pk_add_f32 v[98:99], v[98:99], 1.0 op_sel_hi:[1,0]
	v_rcp_f32_e32 v0, v99
	s_nop 0
	v_mul_f32_e32 v83, v83, v0
	v_rcp_f32_e32 v0, v98
	s_nop 0
	v_mul_f32_e32 v82, v82, v0
	v_mul_f32_e32 v0, 0xbfb8aa3b, v84
	v_pk_mul_f32 v[66:67], v[66:67], v[82:83]
	v_exp_f32_e32 v82, v0
	v_mul_f32_e32 v0, 0xbfb8aa3b, v85
	v_exp_f32_e32 v83, v0
	v_cvt_pk_bf16_f32 v66, v66, v67
	v_pk_add_f32 v[82:83], v[82:83], 1.0 op_sel_hi:[1,0]
	v_rcp_f32_e32 v0, v83
	s_nop 0
	v_mul_f32_e32 v83, v85, v0
	v_rcp_f32_e32 v0, v82
	s_nop 0
	v_mul_f32_e32 v82, v84, v0
	v_pk_mul_f32 v[68:69], v[68:69], v[82:83]
	v_mul_f32_e32 v0, 0xbfb8aa3b, v86
	v_cvt_pk_bf16_f32 v67, v68, v69
	v_exp_f32_e32 v68, v0
	v_mul_f32_e32 v0, 0xbfb8aa3b, v87
	v_exp_f32_e32 v69, v0
	s_nop 0
	v_pk_add_f32 v[68:69], v[68:69], 1.0 op_sel_hi:[1,0]
	v_rcp_f32_e32 v0, v69
	s_nop 0
	v_mul_f32_e32 v69, v87, v0
	v_rcp_f32_e32 v0, v68
	s_nop 0
	v_mul_f32_e32 v68, v86, v0
	v_mul_f32_e32 v0, 0xbfb8aa3b, v88
	v_pk_mul_f32 v[68:69], v[70:71], v[68:69]
	v_exp_f32_e32 v70, v0
	v_mul_f32_e32 v0, 0xbfb8aa3b, v89
	v_exp_f32_e32 v71, v0
	v_cvt_pk_bf16_f32 v68, v68, v69
	s_nop 1
	v_permlane32_swap_b32_e32 v66, v68
	v_pk_add_f32 v[70:71], v[70:71], 1.0 op_sel_hi:[1,0]
	v_rcp_f32_e32 v0, v71
	s_nop 0
	v_mul_f32_e32 v71, v89, v0
	v_rcp_f32_e32 v0, v70
	s_nop 0
	v_mul_f32_e32 v70, v88, v0
	v_pk_mul_f32 v[70:71], v[72:73], v[70:71]
	v_mul_f32_e32 v0, 0xbfb8aa3b, v90
	v_cvt_pk_bf16_f32 v69, v70, v71
	s_nop 1
	v_permlane32_swap_b32_e32 v67, v69
	global_store_dwordx4 v[132:133], v[66:69], off offset:64
	s_nop 1
	v_exp_f32_e32 v66, v0
	v_mul_f32_e32 v0, 0xbfb8aa3b, v91
	v_exp_f32_e32 v67, v0
	s_nop 0
	v_pk_add_f32 v[66:67], v[66:67], 1.0 op_sel_hi:[1,0]
	v_rcp_f32_e32 v0, v67
	s_nop 0
	v_mul_f32_e32 v67, v91, v0
	v_rcp_f32_e32 v0, v66
	s_nop 0
	v_mul_f32_e32 v66, v90, v0
	v_mul_f32_e32 v0, 0xbfb8aa3b, v92
	v_exp_f32_e32 v68, v0
	v_mul_f32_e32 v0, 0xbfb8aa3b, v93
	v_exp_f32_e32 v69, v0
	v_pk_mul_f32 v[66:67], v[74:75], v[66:67]
	v_pk_add_f32 v[68:69], v[68:69], 1.0 op_sel_hi:[1,0]
	s_nop 2
	v_cvt_pk_bf16_f32 v66, v66, v67
	v_rcp_f32_e32 v0, v69
	s_nop 0
	v_mul_f32_e32 v69, v93, v0
	v_rcp_f32_e32 v0, v68
	s_nop 0
	v_mul_f32_e32 v68, v92, v0
	v_pk_mul_f32 v[68:69], v[76:77], v[68:69]
	v_mul_f32_e32 v0, 0xbfb8aa3b, v94
	v_cvt_pk_bf16_f32 v67, v68, v69
	v_exp_f32_e32 v68, v0
	v_mul_f32_e32 v0, 0xbfb8aa3b, v95
	v_exp_f32_e32 v69, v0
	s_nop 0
	v_pk_add_f32 v[68:69], v[68:69], 1.0 op_sel_hi:[1,0]
	v_rcp_f32_e32 v0, v69
	s_nop 0
	v_mul_f32_e32 v69, v95, v0
	v_rcp_f32_e32 v0, v68
	s_nop 0
	v_mul_f32_e32 v68, v94, v0
	v_mul_f32_e32 v0, 0xbfb8aa3b, v96
	v_exp_f32_e32 v70, v0
	v_mul_f32_e32 v0, 0xbfb8aa3b, v97
	v_exp_f32_e32 v71, v0
	v_pk_mul_f32 v[68:69], v[78:79], v[68:69]
	v_pk_add_f32 v[70:71], v[70:71], 1.0 op_sel_hi:[1,0]
	s_nop 2
	v_cvt_pk_bf16_f32 v68, v68, v69
	s_nop 1
	v_permlane32_swap_b32_e32 v66, v68
	s_nop 4
	v_rcp_f32_e32 v0, v71
	s_nop 0
	v_mul_f32_e32 v71, v97, v0
	v_rcp_f32_e32 v0, v70
	s_nop 0
	v_mul_f32_e32 v70, v96, v0
	v_pk_mul_f32 v[70:71], v[80:81], v[70:71]
	v_or_b32_e32 v0, 32, v134
	v_cvt_pk_bf16_f32 v69, v70, v71
	s_nop 1
	v_permlane32_swap_b32_e32 v67, v69
	global_store_dwordx4 v[132:133], v[66:69], off offset:96
	s_nop 1
	v_mad_i64_i32 v[66:67], s[6:7], v0, s8, v[130:131]
	v_mul_f32_e32 v0, 0xbfb8aa3b, v50
	v_exp_f32_e32 v68, v0
	v_mul_f32_e32 v0, 0xbfb8aa3b, v51
	v_exp_f32_e32 v69, v0
	s_nop 0
	v_pk_add_f32 v[68:69], v[68:69], 1.0 op_sel_hi:[1,0]
	v_rcp_f32_e32 v0, v69
	s_nop 0
	v_mul_f32_e32 v51, v51, v0
	v_rcp_f32_e32 v0, v68
	s_nop 0
	v_mul_f32_e32 v50, v50, v0
	v_mul_f32_e32 v0, 0xbfb8aa3b, v52
	v_pk_mul_f32 v[34:35], v[34:35], v[50:51]
	v_exp_f32_e32 v50, v0
	v_mul_f32_e32 v0, 0xbfb8aa3b, v53
	v_exp_f32_e32 v51, v0
	v_cvt_pk_bf16_f32 v34, v34, v35
	v_pk_add_f32 v[50:51], v[50:51], 1.0 op_sel_hi:[1,0]
	v_rcp_f32_e32 v0, v51
	s_nop 0
	v_mul_f32_e32 v51, v53, v0
	v_rcp_f32_e32 v0, v50
	s_nop 0
	v_mul_f32_e32 v50, v52, v0
	v_pk_mul_f32 v[36:37], v[36:37], v[50:51]
	v_mul_f32_e32 v0, 0xbfb8aa3b, v54
	v_cvt_pk_bf16_f32 v35, v36, v37
	v_exp_f32_e32 v36, v0
	v_mul_f32_e32 v0, 0xbfb8aa3b, v55
	v_exp_f32_e32 v37, v0
	s_nop 0
	v_pk_add_f32 v[36:37], v[36:37], 1.0 op_sel_hi:[1,0]
	v_rcp_f32_e32 v0, v37
	s_nop 0
	v_mul_f32_e32 v37, v55, v0
	v_rcp_f32_e32 v0, v36
	s_nop 0
	v_mul_f32_e32 v36, v54, v0
	v_mul_f32_e32 v0, 0xbfb8aa3b, v56
	v_pk_mul_f32 v[36:37], v[38:39], v[36:37]
	v_exp_f32_e32 v38, v0
	v_mul_f32_e32 v0, 0xbfb8aa3b, v57
	v_exp_f32_e32 v39, v0
	v_cvt_pk_bf16_f32 v36, v36, v37
	s_nop 1
	v_permlane32_swap_b32_e32 v34, v36
	v_pk_add_f32 v[38:39], v[38:39], 1.0 op_sel_hi:[1,0]
	v_rcp_f32_e32 v0, v39
	s_nop 0
	v_mul_f32_e32 v39, v57, v0
	v_rcp_f32_e32 v0, v38
	s_nop 0
	v_mul_f32_e32 v38, v56, v0
	v_pk_mul_f32 v[38:39], v[40:41], v[38:39]
	v_mul_f32_e32 v0, 0xbfb8aa3b, v58
	v_cvt_pk_bf16_f32 v37, v38, v39
	s_nop 1
	v_permlane32_swap_b32_e32 v35, v37
	global_store_dwordx4 v[66:67], v[34:37], off
	s_nop 1
	v_exp_f32_e32 v34, v0
	v_mul_f32_e32 v0, 0xbfb8aa3b, v59
	v_exp_f32_e32 v35, v0
	s_nop 0
	v_pk_add_f32 v[34:35], v[34:35], 1.0 op_sel_hi:[1,0]
	v_rcp_f32_e32 v0, v35
	s_nop 0
	v_mul_f32_e32 v35, v59, v0
	v_rcp_f32_e32 v0, v34
	s_nop 0
	v_mul_f32_e32 v34, v58, v0
	v_mul_f32_e32 v0, 0xbfb8aa3b, v60
	v_exp_f32_e32 v36, v0
	v_mul_f32_e32 v0, 0xbfb8aa3b, v61
	v_exp_f32_e32 v37, v0
	v_pk_mul_f32 v[34:35], v[42:43], v[34:35]
	v_pk_add_f32 v[36:37], v[36:37], 1.0 op_sel_hi:[1,0]
	s_nop 2
	v_cvt_pk_bf16_f32 v34, v34, v35
	v_rcp_f32_e32 v0, v37
	s_nop 0
	v_mul_f32_e32 v37, v61, v0
	v_rcp_f32_e32 v0, v36
	s_nop 0
	v_mul_f32_e32 v36, v60, v0
	v_pk_mul_f32 v[36:37], v[44:45], v[36:37]
	v_mul_f32_e32 v0, 0xbfb8aa3b, v62
	v_cvt_pk_bf16_f32 v35, v36, v37
	v_exp_f32_e32 v36, v0
	v_mul_f32_e32 v0, 0xbfb8aa3b, v63
	v_exp_f32_e32 v37, v0
	s_nop 0
	v_pk_add_f32 v[36:37], v[36:37], 1.0 op_sel_hi:[1,0]
	v_rcp_f32_e32 v0, v37
	s_nop 0
	v_mul_f32_e32 v37, v63, v0
	v_rcp_f32_e32 v0, v36
	s_nop 0
	v_mul_f32_e32 v36, v62, v0
	v_mul_f32_e32 v0, 0xbfb8aa3b, v64
	v_exp_f32_e32 v38, v0
	v_mul_f32_e32 v0, 0xbfb8aa3b, v65
	v_exp_f32_e32 v39, v0
	v_pk_mul_f32 v[36:37], v[46:47], v[36:37]
	v_pk_add_f32 v[38:39], v[38:39], 1.0 op_sel_hi:[1,0]
	s_nop 2
	v_cvt_pk_bf16_f32 v36, v36, v37
	s_nop 1
	v_permlane32_swap_b32_e32 v34, v36
	s_nop 4
	v_rcp_f32_e32 v0, v39
	s_nop 0
	v_mul_f32_e32 v39, v65, v0
	v_rcp_f32_e32 v0, v38
	s_nop 0
	v_mul_f32_e32 v38, v64, v0
	v_pk_mul_f32 v[38:39], v[48:49], v[38:39]
	v_mul_f32_e32 v0, 0xbfb8aa3b, v18
	v_cvt_pk_bf16_f32 v37, v38, v39
	s_nop 1
	v_permlane32_swap_b32_e32 v35, v37
	global_store_dwordx4 v[66:67], v[34:37], off offset:32
	s_nop 1
	v_exp_f32_e32 v34, v0
	v_mul_f32_e32 v0, 0xbfb8aa3b, v19
	v_exp_f32_e32 v35, v0
	s_nop 0
	v_pk_add_f32 v[34:35], v[34:35], 1.0 op_sel_hi:[1,0]
	v_rcp_f32_e32 v0, v35
	s_nop 0
	v_mul_f32_e32 v19, v19, v0
	v_rcp_f32_e32 v0, v34
	s_nop 0
	v_mul_f32_e32 v18, v18, v0
	v_mul_f32_e32 v0, 0xbfb8aa3b, v20
	v_pk_mul_f32 v[2:3], v[2:3], v[18:19]
	v_exp_f32_e32 v18, v0
	v_mul_f32_e32 v0, 0xbfb8aa3b, v21
	v_exp_f32_e32 v19, v0
	v_cvt_pk_bf16_f32 v2, v2, v3
	v_pk_add_f32 v[18:19], v[18:19], 1.0 op_sel_hi:[1,0]
	v_rcp_f32_e32 v0, v19
	s_nop 0
	v_mul_f32_e32 v19, v21, v0
	v_rcp_f32_e32 v0, v18
	s_nop 0
	v_mul_f32_e32 v18, v20, v0
	v_pk_mul_f32 v[4:5], v[4:5], v[18:19]
	v_mul_f32_e32 v0, 0xbfb8aa3b, v22
	v_cvt_pk_bf16_f32 v3, v4, v5
	v_exp_f32_e32 v4, v0
	v_mul_f32_e32 v0, 0xbfb8aa3b, v23
	v_exp_f32_e32 v5, v0
	s_nop 0
	v_pk_add_f32 v[4:5], v[4:5], 1.0 op_sel_hi:[1,0]
	v_rcp_f32_e32 v0, v5
	s_nop 0
	v_mul_f32_e32 v5, v23, v0
	v_rcp_f32_e32 v0, v4
	s_nop 0
	v_mul_f32_e32 v4, v22, v0
	v_mul_f32_e32 v0, 0xbfb8aa3b, v24
	v_pk_mul_f32 v[4:5], v[6:7], v[4:5]
	v_exp_f32_e32 v6, v0
	v_mul_f32_e32 v0, 0xbfb8aa3b, v25
	v_exp_f32_e32 v7, v0
	v_cvt_pk_bf16_f32 v4, v4, v5
	s_nop 1
	v_permlane32_swap_b32_e32 v2, v4
	v_pk_add_f32 v[6:7], v[6:7], 1.0 op_sel_hi:[1,0]
	v_rcp_f32_e32 v0, v7
	s_nop 0
	v_mul_f32_e32 v7, v25, v0
	v_rcp_f32_e32 v0, v6
	s_nop 0
	v_mul_f32_e32 v6, v24, v0
	v_pk_mul_f32 v[6:7], v[8:9], v[6:7]
	v_mul_f32_e32 v0, 0xbfb8aa3b, v26
	v_cvt_pk_bf16_f32 v5, v6, v7
	s_nop 1
	v_permlane32_swap_b32_e32 v3, v5
	global_store_dwordx4 v[66:67], v[2:5], off offset:64
	s_nop 1
	v_exp_f32_e32 v2, v0
	v_mul_f32_e32 v0, 0xbfb8aa3b, v27
	v_exp_f32_e32 v3, v0
	s_nop 0
	v_pk_add_f32 v[2:3], v[2:3], 1.0 op_sel_hi:[1,0]
	v_rcp_f32_e32 v0, v3
	s_nop 0
	v_mul_f32_e32 v3, v27, v0
	v_rcp_f32_e32 v0, v2
	s_nop 0
	v_mul_f32_e32 v2, v26, v0
	v_mul_f32_e32 v0, 0xbfb8aa3b, v28
	v_exp_f32_e32 v4, v0
	v_mul_f32_e32 v0, 0xbfb8aa3b, v29
	v_exp_f32_e32 v5, v0
	v_pk_mul_f32 v[2:3], v[10:11], v[2:3]
	v_pk_add_f32 v[4:5], v[4:5], 1.0 op_sel_hi:[1,0]
	s_nop 2
	v_cvt_pk_bf16_f32 v2, v2, v3
	v_rcp_f32_e32 v0, v5
	s_nop 0
	v_mul_f32_e32 v5, v29, v0
	v_rcp_f32_e32 v0, v4
	s_nop 0
	v_mul_f32_e32 v4, v28, v0
	v_pk_mul_f32 v[4:5], v[12:13], v[4:5]
	v_mul_f32_e32 v0, 0xbfb8aa3b, v30
	v_cvt_pk_bf16_f32 v3, v4, v5
	v_exp_f32_e32 v4, v0
	v_mul_f32_e32 v0, 0xbfb8aa3b, v31
	v_exp_f32_e32 v5, v0
	s_nop 0
	v_pk_add_f32 v[4:5], v[4:5], 1.0 op_sel_hi:[1,0]
	v_rcp_f32_e32 v0, v5
	s_nop 0
	v_mul_f32_e32 v5, v31, v0
	v_rcp_f32_e32 v0, v4
	s_nop 0
	v_mul_f32_e32 v4, v30, v0
	v_mul_f32_e32 v0, 0xbfb8aa3b, v32
	v_exp_f32_e32 v6, v0
	v_mul_f32_e32 v0, 0xbfb8aa3b, v33
	v_exp_f32_e32 v7, v0
	v_pk_mul_f32 v[4:5], v[14:15], v[4:5]
	v_pk_add_f32 v[6:7], v[6:7], 1.0 op_sel_hi:[1,0]
	s_nop 2
	v_cvt_pk_bf16_f32 v4, v4, v5
	s_nop 1
	v_permlane32_swap_b32_e32 v2, v4
	s_nop 4
	v_rcp_f32_e32 v0, v7
	s_nop 0
	v_mul_f32_e32 v7, v33, v0
	s_nop 1
	s_mov_b64 s[6:7], 0
	s_nop 4
	v_rcp_f32_e32 v0, v6
	s_nop 0
	v_mul_f32_e32 v6, v32, v0
	v_pk_mul_f32 v[6:7], v[16:17], v[6:7]
	s_nop 0
	v_cvt_pk_bf16_f32 v5, v6, v7
	s_nop 1
	v_permlane32_swap_b32_e32 v3, v5
	global_store_dwordx4 v[66:67], v[2:5], off offset:96

.LBB0_135:
	v_mul_f32_e32 v0, 0xbfb8aa3b, v114
	s_waitcnt vmcnt(2)
	v_exp_f32_e32 v158, v0
	v_mul_f32_e32 v0, 0xbfb8aa3b, v115
	v_exp_f32_e32 v159, v0
	v_mul_f32_e32 v0, 0xbfb8aa3b, v116
	v_exp_f32_e32 v156, v0
	v_mul_f32_e32 v0, 0xbfb8aa3b, v117
	v_exp_f32_e32 v157, v0
	v_mul_f32_e32 v0, 0xbfb8aa3b, v118
	v_exp_f32_e32 v154, v0
	v_mul_f32_e32 v0, 0xbfb8aa3b, v119
	v_exp_f32_e32 v155, v0
	v_mul_f32_e32 v0, 0xbfb8aa3b, v120
	v_exp_f32_e32 v152, v0
	v_mul_f32_e32 v0, 0xbfb8aa3b, v121
	v_exp_f32_e32 v153, v0
	v_mul_f32_e32 v0, 0xbfb8aa3b, v122
	v_exp_f32_e32 v150, v0
	v_mul_f32_e32 v0, 0xbfb8aa3b, v123
	v_exp_f32_e32 v151, v0
	v_mul_f32_e32 v0, 0xbfb8aa3b, v124
	v_exp_f32_e32 v148, v0
	v_mul_f32_e32 v0, 0xbfb8aa3b, v125
	v_exp_f32_e32 v149, v0
	v_mul_f32_e32 v0, 0xbfb8aa3b, v126
	v_exp_f32_e32 v146, v0
	v_mul_f32_e32 v0, 0xbfb8aa3b, v127
	v_exp_f32_e32 v147, v0
	v_mul_f32_e32 v0, 0xbfb8aa3b, v128
	v_exp_f32_e32 v128, v0
	v_mul_f32_e32 v0, 0xbfb8aa3b, v129
	v_exp_f32_e32 v129, v0
	v_mul_f32_e32 v0, 0xbfb8aa3b, v98
	v_exp_f32_e32 v126, v0
	v_mul_f32_e32 v0, 0xbfb8aa3b, v99
	v_exp_f32_e32 v127, v0
	v_mul_f32_e32 v0, 0xbfb8aa3b, v100
	v_exp_f32_e32 v124, v0
	v_mul_f32_e32 v0, 0xbfb8aa3b, v101
	v_exp_f32_e32 v125, v0
	v_mul_f32_e32 v0, 0xbfb8aa3b, v102
	v_exp_f32_e32 v122, v0
	v_mul_f32_e32 v0, 0xbfb8aa3b, v103
	v_exp_f32_e32 v123, v0
	v_mul_f32_e32 v0, 0xbfb8aa3b, v104
	v_exp_f32_e32 v120, v0
	v_mul_f32_e32 v0, 0xbfb8aa3b, v105
	v_exp_f32_e32 v121, v0
	v_mul_f32_e32 v0, 0xbfb8aa3b, v106
	v_exp_f32_e32 v118, v0
	v_mul_f32_e32 v0, 0xbfb8aa3b, v107
	v_exp_f32_e32 v119, v0
	v_mul_f32_e32 v0, 0xbfb8aa3b, v108
	v_exp_f32_e32 v116, v0
	v_mul_f32_e32 v0, 0xbfb8aa3b, v109
	v_exp_f32_e32 v117, v0
	v_mul_f32_e32 v0, 0xbfb8aa3b, v110
	v_exp_f32_e32 v114, v0
	v_mul_f32_e32 v0, 0xbfb8aa3b, v111
	v_exp_f32_e32 v115, v0
	v_mul_f32_e32 v0, 0xbfb8aa3b, v112
	v_exp_f32_e32 v110, v0
	v_mul_f32_e32 v0, 0xbfb8aa3b, v113
	v_exp_f32_e32 v111, v0
	v_mul_f32_e32 v0, 0xbfb8aa3b, v82
	v_exp_f32_e32 v108, v0
	v_mul_f32_e32 v0, 0xbfb8aa3b, v83
	v_exp_f32_e32 v109, v0
	v_mul_f32_e32 v0, 0xbfb8aa3b, v84
	v_exp_f32_e32 v106, v0
	v_mul_f32_e32 v0, 0xbfb8aa3b, v85
	v_exp_f32_e32 v107, v0
	v_mul_f32_e32 v0, 0xbfb8aa3b, v86
	v_exp_f32_e32 v104, v0
	v_mul_f32_e32 v0, 0xbfb8aa3b, v87
	v_exp_f32_e32 v105, v0
	v_mul_f32_e32 v0, 0xbfb8aa3b, v88
	v_exp_f32_e32 v102, v0
	v_mul_f32_e32 v0, 0xbfb8aa3b, v89
	v_exp_f32_e32 v103, v0
	v_mul_f32_e32 v0, 0xbfb8aa3b, v90
	v_exp_f32_e32 v100, v0
	v_mul_f32_e32 v0, 0xbfb8aa3b, v91
	v_exp_f32_e32 v101, v0
	v_mul_f32_e32 v0, 0xbfb8aa3b, v92
	v_exp_f32_e32 v98, v0
	v_mul_f32_e32 v0, 0xbfb8aa3b, v93
	v_exp_f32_e32 v99, v0
	v_mul_f32_e32 v0, 0xbfb8aa3b, v94
	v_exp_f32_e32 v92, v0
	v_mul_f32_e32 v0, 0xbfb8aa3b, v95
	v_exp_f32_e32 v93, v0
	v_mul_f32_e32 v0, 0xbfb8aa3b, v96
	v_exp_f32_e32 v90, v0
	v_mul_f32_e32 v0, 0xbfb8aa3b, v97
	v_exp_f32_e32 v91, v0
	v_mul_f32_e32 v0, 0xbfb8aa3b, v66
	v_exp_f32_e32 v88, v0
	v_mul_f32_e32 v0, 0xbfb8aa3b, v67
	v_exp_f32_e32 v89, v0
	v_mul_f32_e32 v0, 0xbfb8aa3b, v68
	v_exp_f32_e32 v86, v0
	v_mul_f32_e32 v0, 0xbfb8aa3b, v69
	v_exp_f32_e32 v87, v0
	v_mul_f32_e32 v0, 0xbfb8aa3b, v70
	v_exp_f32_e32 v84, v0
	v_mul_f32_e32 v0, 0xbfb8aa3b, v71
	v_exp_f32_e32 v85, v0
	v_mul_f32_e32 v0, 0xbfb8aa3b, v72
	v_exp_f32_e32 v82, v0
	v_mul_f32_e32 v0, 0xbfb8aa3b, v73
	v_exp_f32_e32 v83, v0
	v_mul_f32_e32 v0, 0xbfb8aa3b, v74
	v_exp_f32_e32 v72, v0
	v_mul_f32_e32 v0, 0xbfb8aa3b, v75
	v_exp_f32_e32 v73, v0
	v_mul_f32_e32 v0, 0xbfb8aa3b, v76
	v_exp_f32_e32 v70, v0
	v_mul_f32_e32 v0, 0xbfb8aa3b, v77
	v_exp_f32_e32 v71, v0
	v_mul_f32_e32 v0, 0xbfb8aa3b, v78
	v_exp_f32_e32 v68, v0
	v_mul_f32_e32 v0, 0xbfb8aa3b, v79
	v_exp_f32_e32 v69, v0
	v_mul_f32_e32 v0, 0xbfb8aa3b, v80
	v_exp_f32_e32 v66, v0
	v_mul_f32_e32 v0, 0xbfb8aa3b, v81
	v_pk_add_f32 v[74:75], v[158:159], 1.0 op_sel_hi:[1,0]
	v_exp_f32_e32 v67, v0
	s_nop 1
	v_pk_add_f32 v[114:115], v[114:115], 1.0 op_sel_hi:[1,0]
	v_pk_add_f32 v[110:111], v[110:111], 1.0 op_sel_hi:[1,0]
	v_pk_add_f32 v[108:109], v[108:109], 1.0 op_sel_hi:[1,0]
	v_rcp_f32_e32 v0, v75
	s_nop 0
	v_mul_f32_e32 v0, 1.0, v0
	s_nop 1
	v_pk_add_f32 v[106:107], v[106:107], 1.0 op_sel_hi:[1,0]
	v_pk_add_f32 v[104:105], v[104:105], 1.0 op_sel_hi:[1,0]
	v_pk_add_f32 v[102:103], v[102:103], 1.0 op_sel_hi:[1,0]
	v_rcp_f32_e32 v75, v74
	s_nop 0
	v_mul_f32_e32 v74, 1.0, v75
	v_cvt_pk_bf16_f32 v0, v74, v0
	v_pk_add_f32 v[74:75], v[156:157], 1.0 op_sel_hi:[1,0]
	v_pk_add_f32 v[100:101], v[100:101], 1.0 op_sel_hi:[1,0]
	s_nop 1
	v_pk_add_f32 v[98:99], v[98:99], 1.0 op_sel_hi:[1,0]
	v_pk_add_f32 v[92:93], v[92:93], 1.0 op_sel_hi:[1,0]
	v_pk_add_f32 v[90:91], v[90:91], 1.0 op_sel_hi:[1,0]
	v_rcp_f32_e32 v76, v75
	s_nop 0
	v_mul_f32_e32 v75, 1.0, v76
	s_nop 1
	v_pk_add_f32 v[88:89], v[88:89], 1.0 op_sel_hi:[1,0]
	v_pk_add_f32 v[86:87], v[86:87], 1.0 op_sel_hi:[1,0]
	v_pk_add_f32 v[84:85], v[84:85], 1.0 op_sel_hi:[1,0]
	v_rcp_f32_e32 v76, v74
	s_nop 0
	v_mul_f32_e32 v74, 1.0, v76
	v_pk_add_f32 v[76:77], v[154:155], 1.0 op_sel_hi:[1,0]
	v_cvt_pk_bf16_f32 v74, v74, v75
	s_nop 1
	v_pk_add_f32 v[82:83], v[82:83], 1.0 op_sel_hi:[1,0]
	v_pk_add_f32 v[72:73], v[72:73], 1.0 op_sel_hi:[1,0]
	v_pk_add_f32 v[70:71], v[70:71], 1.0 op_sel_hi:[1,0]
	v_rcp_f32_e32 v75, v77
	s_nop 0
	v_mul_f32_e32 v75, 1.0, v75
	s_nop 1
	v_pk_add_f32 v[68:69], v[68:69], 1.0 op_sel_hi:[1,0]
	v_pk_add_f32 v[66:67], v[66:67], 1.0 op_sel_hi:[1,0]
	s_add_i32 s27, s27, 1
	s_nop 4
	v_rcp_f32_e32 v77, v76
	s_nop 0
	v_mul_f32_e32 v76, 1.0, v77
	v_cvt_pk_bf16_f32 v75, v76, v75
	v_pk_add_f32 v[76:77], v[152:153], 1.0 op_sel_hi:[1,0]
	s_cmp_lg_u32 s27, 3
	s_nop 4
	v_rcp_f32_e32 v78, v77
	s_nop 0
	v_mul_f32_e32 v77, 1.0, v78
	v_rcp_f32_e32 v78, v76
	s_nop 0
	v_mul_f32_e32 v76, 1.0, v78
	v_pk_add_f32 v[78:79], v[150:151], 1.0 op_sel_hi:[1,0]
	v_cvt_pk_bf16_f32 v76, v76, v77
	v_rcp_f32_e32 v77, v79
	s_nop 0
	v_mul_f32_e32 v77, 1.0, v77
	v_rcp_f32_e32 v79, v78
	s_nop 0
	v_mul_f32_e32 v78, 1.0, v79
	v_cvt_pk_bf16_f32 v77, v78, v77
	v_pk_add_f32 v[78:79], v[148:149], 1.0 op_sel_hi:[1,0]
	v_rcp_f32_e32 v80, v79
	s_nop 0
	v_mul_f32_e32 v79, 1.0, v80
	v_rcp_f32_e32 v80, v78
	s_nop 0
	v_mul_f32_e32 v78, 1.0, v80
	v_pk_add_f32 v[80:81], v[146:147], 1.0 op_sel_hi:[1,0]
	v_cvt_pk_bf16_f32 v78, v78, v79
	v_rcp_f32_e32 v79, v81
	s_nop 0
	v_mul_f32_e32 v79, 1.0, v79
	v_rcp_f32_e32 v81, v80
	s_nop 0
	v_mul_f32_e32 v80, 1.0, v81
	v_cvt_pk_bf16_f32 v79, v80, v79
	v_pk_add_f32 v[80:81], v[128:129], 1.0 op_sel_hi:[1,0]
	v_rcp_f32_e32 v94, v81
	s_nop 0
	v_mul_f32_e32 v81, 1.0, v94
	v_rcp_f32_e32 v94, v80
	s_nop 0
	v_mul_f32_e32 v80, 1.0, v94
	v_pk_add_f32 v[94:95], v[126:127], 1.0 op_sel_hi:[1,0]
	v_cvt_pk_bf16_f32 v80, v80, v81
	v_rcp_f32_e32 v81, v95
	s_nop 0
	v_mul_f32_e32 v81, 1.0, v81
	v_rcp_f32_e32 v95, v94
	s_nop 0
	v_mul_f32_e32 v94, 1.0, v95
	v_cvt_pk_bf16_f32 v81, v94, v81
	v_pk_add_f32 v[94:95], v[124:125], 1.0 op_sel_hi:[1,0]
	v_rcp_f32_e32 v96, v95
	s_nop 0
	v_mul_f32_e32 v95, 1.0, v96
	v_rcp_f32_e32 v96, v94
	s_nop 0
	v_mul_f32_e32 v94, 1.0, v96
	v_pk_add_f32 v[96:97], v[122:123], 1.0 op_sel_hi:[1,0]
	v_cvt_pk_bf16_f32 v94, v94, v95
	v_rcp_f32_e32 v95, v97
	s_nop 0
	v_mul_f32_e32 v95, 1.0, v95
	v_rcp_f32_e32 v97, v96
	s_nop 0
	v_mul_f32_e32 v96, 1.0, v97
	v_cvt_pk_bf16_f32 v95, v96, v95
	v_pk_add_f32 v[96:97], v[120:121], 1.0 op_sel_hi:[1,0]
	v_rcp_f32_e32 v112, v97
	s_nop 0
	v_mul_f32_e32 v97, 1.0, v112
	v_rcp_f32_e32 v112, v96
	s_nop 0
	v_mul_f32_e32 v96, 1.0, v112
	v_pk_add_f32 v[112:113], v[118:119], 1.0 op_sel_hi:[1,0]
	v_cvt_pk_bf16_f32 v96, v96, v97
	v_rcp_f32_e32 v97, v113
	s_nop 0
	v_mul_f32_e32 v97, 1.0, v97
	v_rcp_f32_e32 v113, v112
	s_nop 0
	v_mul_f32_e32 v112, 1.0, v113
	v_cvt_pk_bf16_f32 v97, v112, v97
	v_pk_add_f32 v[112:113], v[116:117], 1.0 op_sel_hi:[1,0]
	v_rcp_f32_e32 v116, v113
	s_nop 0
	v_mul_f32_e32 v113, 1.0, v116
	v_rcp_f32_e32 v116, v112
	s_nop 0
	v_mul_f32_e32 v112, 1.0, v116
	v_cvt_pk_bf16_f32 v112, v112, v113
	v_rcp_f32_e32 v113, v115
	s_nop 0
	v_mul_f32_e32 v113, 1.0, v113
	v_rcp_f32_e32 v115, v114
	s_nop 0
	v_mul_f32_e32 v114, 1.0, v115
	v_cvt_pk_bf16_f32 v113, v114, v113
	v_rcp_f32_e32 v114, v111
	s_nop 0
	v_mul_f32_e32 v111, 1.0, v114
	v_rcp_f32_e32 v114, v110
	s_nop 0
	v_mul_f32_e32 v110, 1.0, v114
	v_cvt_pk_bf16_f32 v110, v110, v111
	v_rcp_f32_e32 v111, v109
	s_nop 0
	v_mul_f32_e32 v109, 1.0, v111
	v_rcp_f32_e32 v111, v108
	s_nop 0
	v_mul_f32_e32 v108, 1.0, v111
	v_cvt_pk_bf16_f32 v108, v108, v109
	v_rcp_f32_e32 v109, v107
	s_nop 0
	v_mul_f32_e32 v107, 1.0, v109
	v_rcp_f32_e32 v109, v106
	s_nop 0
	v_mul_f32_e32 v106, 1.0, v109
	v_cvt_pk_bf16_f32 v106, v106, v107
	v_rcp_f32_e32 v107, v105
	s_nop 0
	v_mul_f32_e32 v105, 1.0, v107
	v_rcp_f32_e32 v107, v104
	s_nop 0
	v_mul_f32_e32 v104, 1.0, v107
	v_cvt_pk_bf16_f32 v104, v104, v105
	s_nop 1
	v_and_b32_e32 v115, 0xffff0000, v144
	v_rcp_f32_e32 v105, v103
	s_nop 0
	v_mul_f32_e32 v103, 1.0, v105
	v_rcp_f32_e32 v105, v102
	s_nop 0
	v_mul_f32_e32 v102, 1.0, v105
	v_cvt_pk_bf16_f32 v102, v102, v103
	s_nop 1
	v_lshlrev_b32_e32 v114, 16, v144
	v_rcp_f32_e32 v103, v101
	s_nop 0
	v_mul_f32_e32 v101, 1.0, v103
	v_rcp_f32_e32 v103, v100
	s_nop 0
	v_mul_f32_e32 v100, 1.0, v103
	v_cvt_pk_bf16_f32 v100, v100, v101
	v_rcp_f32_e32 v101, v99
	s_nop 0
	v_mul_f32_e32 v99, 1.0, v101
	v_rcp_f32_e32 v101, v98
	s_nop 0
	v_mul_f32_e32 v98, 1.0, v101
	v_cvt_pk_bf16_f32 v98, v98, v99
	v_rcp_f32_e32 v99, v93
	s_nop 0
	v_mul_f32_e32 v93, 1.0, v99
	v_rcp_f32_e32 v99, v92
	s_nop 0
	v_mul_f32_e32 v92, 1.0, v99
	v_cvt_pk_bf16_f32 v92, v92, v93
	v_rcp_f32_e32 v93, v91
	s_nop 0
	v_mul_f32_e32 v91, 1.0, v93
	v_rcp_f32_e32 v93, v90
	s_nop 0
	v_mul_f32_e32 v90, 1.0, v93
	v_cvt_pk_bf16_f32 v90, v90, v91
	v_rcp_f32_e32 v91, v89
	s_nop 0
	v_mul_f32_e32 v89, 1.0, v91
	v_rcp_f32_e32 v91, v88
	s_nop 0
	v_mul_f32_e32 v88, 1.0, v91
	v_cvt_pk_bf16_f32 v88, v88, v89
	v_rcp_f32_e32 v89, v87
	s_nop 0
	v_mul_f32_e32 v87, 1.0, v89
	v_rcp_f32_e32 v89, v86
	s_nop 0
	v_mul_f32_e32 v86, 1.0, v89
	v_cvt_pk_bf16_f32 v86, v86, v87
	v_rcp_f32_e32 v87, v85
	s_nop 0
	v_mul_f32_e32 v85, 1.0, v87
	v_rcp_f32_e32 v87, v84
	s_nop 0
	v_mul_f32_e32 v84, 1.0, v87
	v_cvt_pk_bf16_f32 v84, v84, v85
	v_rcp_f32_e32 v85, v83
	s_nop 0
	v_mul_f32_e32 v83, 1.0, v85
	v_rcp_f32_e32 v85, v82
	s_nop 0
	v_mul_f32_e32 v82, 1.0, v85
	v_cvt_pk_bf16_f32 v82, v82, v83
	v_rcp_f32_e32 v83, v73
	s_nop 0
	v_mul_f32_e32 v73, 1.0, v83
	v_rcp_f32_e32 v83, v72
	s_nop 0
	v_mul_f32_e32 v72, 1.0, v83
	v_cvt_pk_bf16_f32 v72, v72, v73
	v_rcp_f32_e32 v73, v71
	s_nop 0
	v_mul_f32_e32 v71, 1.0, v73
	v_rcp_f32_e32 v73, v70
	s_nop 0
	v_mul_f32_e32 v70, 1.0, v73
	v_cvt_pk_bf16_f32 v70, v70, v71
	v_rcp_f32_e32 v71, v69
	s_nop 0
	v_mul_f32_e32 v69, 1.0, v71
	v_rcp_f32_e32 v71, v68
	s_nop 0
	v_mul_f32_e32 v68, 1.0, v71
	v_cvt_pk_bf16_f32 v68, v68, v69
	v_rcp_f32_e32 v69, v67
	s_nop 0
	v_mul_f32_e32 v67, 1.0, v69
	v_rcp_f32_e32 v69, v66
	s_nop 0
	v_mul_f32_e32 v66, 1.0, v69
	v_cvt_pk_bf16_f32 v69, v66, v67
	v_lshlrev_b32_e32 v66, 16, v0
	v_and_b32_e32 v67, 0xffff0000, v0
	v_pk_mul_f32 v[116:117], v[50:51], v[66:67]
	v_pk_fma_f32 v[50:51], v[50:51], v[66:67], v[114:115]
	v_lshlrev_b32_e32 v66, 16, v145
	v_cndmask_b32_e64 v0, v51, v117, s[0:1]
	v_cndmask_b32_e64 v50, v50, v116, s[0:1]
	v_cvt_pk_bf16_f32 v144, v50, v0
	v_lshlrev_b32_e32 v50, 16, v74
	v_and_b32_e32 v51, 0xffff0000, v74
	v_and_b32_e32 v67, 0xffff0000, v145
	v_pk_mul_f32 v[114:115], v[52:53], v[50:51]
	v_pk_fma_f32 v[50:51], v[52:53], v[50:51], v[66:67]
	v_lshlrev_b32_e32 v52, 16, v247
	v_cndmask_b32_e64 v0, v51, v115, s[0:1]
	v_cndmask_b32_e64 v50, v50, v114, s[0:1]
	v_cvt_pk_bf16_f32 v145, v50, v0
	v_lshlrev_b32_e32 v50, 16, v75
	v_and_b32_e32 v51, 0xffff0000, v75
	v_and_b32_e32 v53, 0xffff0000, v247
	v_pk_mul_f32 v[66:67], v[54:55], v[50:51]
	v_pk_fma_f32 v[50:51], v[54:55], v[50:51], v[52:53]
	v_lshlrev_b32_e32 v52, 16, v248
	v_cndmask_b32_e64 v0, v51, v67, s[0:1]
	v_cndmask_b32_e64 v50, v50, v66, s[0:1]
	v_cvt_pk_bf16_f32 v247, v50, v0
	v_lshlrev_b32_e32 v50, 16, v76
	v_and_b32_e32 v51, 0xffff0000, v76
	v_and_b32_e32 v53, 0xffff0000, v248
	v_pk_mul_f32 v[54:55], v[56:57], v[50:51]
	v_pk_fma_f32 v[50:51], v[56:57], v[50:51], v[52:53]
	v_lshlrev_b32_e32 v52, 16, v142
	v_cndmask_b32_e64 v0, v51, v55, s[0:1]
	v_cndmask_b32_e64 v50, v50, v54, s[0:1]
	v_cvt_pk_bf16_f32 v248, v50, v0
	v_lshlrev_b32_e32 v50, 16, v77
	v_and_b32_e32 v51, 0xffff0000, v77
	v_and_b32_e32 v53, 0xffff0000, v142
	v_pk_mul_f32 v[54:55], v[58:59], v[50:51]
	v_pk_fma_f32 v[50:51], v[58:59], v[50:51], v[52:53]
	v_lshlrev_b32_e32 v52, 16, v143
	v_cndmask_b32_e64 v0, v51, v55, s[0:1]
	v_cndmask_b32_e64 v50, v50, v54, s[0:1]
	v_cvt_pk_bf16_f32 v142, v50, v0
	v_lshlrev_b32_e32 v50, 16, v78
	v_and_b32_e32 v51, 0xffff0000, v78
	v_and_b32_e32 v53, 0xffff0000, v143
	v_pk_mul_f32 v[54:55], v[60:61], v[50:51]
	v_pk_fma_f32 v[50:51], v[60:61], v[50:51], v[52:53]
	v_lshlrev_b32_e32 v52, 16, v245
	v_cndmask_b32_e64 v0, v51, v55, s[0:1]
	v_cndmask_b32_e64 v50, v50, v54, s[0:1]
	v_cvt_pk_bf16_f32 v143, v50, v0
	v_lshlrev_b32_e32 v50, 16, v79
	v_and_b32_e32 v51, 0xffff0000, v79
	v_and_b32_e32 v53, 0xffff0000, v245
	v_pk_mul_f32 v[54:55], v[62:63], v[50:51]
	v_pk_fma_f32 v[50:51], v[62:63], v[50:51], v[52:53]
	v_lshlrev_b32_e32 v52, 16, v246
	v_cndmask_b32_e64 v0, v51, v55, s[0:1]
	v_cndmask_b32_e64 v50, v50, v54, s[0:1]
	v_cvt_pk_bf16_f32 v245, v50, v0
	v_lshlrev_b32_e32 v50, 16, v80
	v_and_b32_e32 v51, 0xffff0000, v80
	v_and_b32_e32 v53, 0xffff0000, v246
	v_pk_mul_f32 v[54:55], v[64:65], v[50:51]
	v_pk_fma_f32 v[50:51], v[64:65], v[50:51], v[52:53]
	v_lshlrev_b32_e32 v52, 16, v140
	v_cndmask_b32_e64 v0, v51, v55, s[0:1]
	v_cndmask_b32_e64 v50, v50, v54, s[0:1]
	v_cvt_pk_bf16_f32 v246, v50, v0
	v_lshlrev_b32_e32 v50, 16, v81
	v_and_b32_e32 v51, 0xffff0000, v81
	v_and_b32_e32 v53, 0xffff0000, v140
	v_pk_mul_f32 v[54:55], v[34:35], v[50:51]
	v_pk_fma_f32 v[34:35], v[34:35], v[50:51], v[52:53]
	v_lshlrev_b32_e32 v50, 16, v141
	v_cndmask_b32_e64 v0, v35, v55, s[0:1]
	v_cndmask_b32_e64 v34, v34, v54, s[0:1]
	v_cvt_pk_bf16_f32 v140, v34, v0
	v_lshlrev_b32_e32 v34, 16, v94
	v_and_b32_e32 v35, 0xffff0000, v94
	v_and_b32_e32 v51, 0xffff0000, v141
	v_pk_mul_f32 v[52:53], v[36:37], v[34:35]
	v_pk_fma_f32 v[34:35], v[36:37], v[34:35], v[50:51]
	v_lshlrev_b32_e32 v36, 16, v225
	v_cndmask_b32_e64 v0, v35, v53, s[0:1]
	v_cndmask_b32_e64 v34, v34, v52, s[0:1]
	v_cvt_pk_bf16_f32 v141, v34, v0
	v_lshlrev_b32_e32 v34, 16, v95
	v_and_b32_e32 v35, 0xffff0000, v95
	v_and_b32_e32 v37, 0xffff0000, v225
	v_pk_mul_f32 v[50:51], v[38:39], v[34:35]
	v_pk_fma_f32 v[34:35], v[38:39], v[34:35], v[36:37]
	v_lshlrev_b32_e32 v36, 16, v226
	v_cndmask_b32_e64 v0, v35, v51, s[0:1]
	v_cndmask_b32_e64 v34, v34, v50, s[0:1]
	v_cvt_pk_bf16_f32 v225, v34, v0
	v_lshlrev_b32_e32 v34, 16, v96
	v_and_b32_e32 v35, 0xffff0000, v96
	v_and_b32_e32 v37, 0xffff0000, v226
	v_pk_mul_f32 v[38:39], v[40:41], v[34:35]
	v_pk_fma_f32 v[34:35], v[40:41], v[34:35], v[36:37]
	v_lshlrev_b32_e32 v36, 16, v138
	v_cndmask_b32_e64 v0, v35, v39, s[0:1]
	v_cndmask_b32_e64 v34, v34, v38, s[0:1]
	v_cvt_pk_bf16_f32 v226, v34, v0
	v_lshlrev_b32_e32 v34, 16, v97
	v_and_b32_e32 v35, 0xffff0000, v97
	v_and_b32_e32 v37, 0xffff0000, v138
	v_pk_mul_f32 v[38:39], v[42:43], v[34:35]
	v_pk_fma_f32 v[34:35], v[42:43], v[34:35], v[36:37]
	v_lshlrev_b32_e32 v36, 16, v139
	v_cndmask_b32_e64 v0, v35, v39, s[0:1]
	v_cndmask_b32_e64 v34, v34, v38, s[0:1]
	v_cvt_pk_bf16_f32 v138, v34, v0
	v_lshlrev_b32_e32 v34, 16, v112
	v_and_b32_e32 v35, 0xffff0000, v112
	v_and_b32_e32 v37, 0xffff0000, v139
	v_pk_mul_f32 v[38:39], v[44:45], v[34:35]
	v_pk_fma_f32 v[34:35], v[44:45], v[34:35], v[36:37]
	v_lshlrev_b32_e32 v36, 16, v223
	v_cndmask_b32_e64 v0, v35, v39, s[0:1]
	v_cndmask_b32_e64 v34, v34, v38, s[0:1]
	v_cvt_pk_bf16_f32 v139, v34, v0
	v_lshlrev_b32_e32 v34, 16, v113
	v_and_b32_e32 v35, 0xffff0000, v113
	v_and_b32_e32 v37, 0xffff0000, v223
	v_pk_mul_f32 v[38:39], v[46:47], v[34:35]
	v_pk_fma_f32 v[34:35], v[46:47], v[34:35], v[36:37]
	v_lshlrev_b32_e32 v36, 16, v224
	v_cndmask_b32_e64 v0, v35, v39, s[0:1]
	v_cndmask_b32_e64 v34, v34, v38, s[0:1]
	v_cvt_pk_bf16_f32 v223, v34, v0
	v_lshlrev_b32_e32 v34, 16, v110
	v_and_b32_e32 v35, 0xffff0000, v110
	v_and_b32_e32 v37, 0xffff0000, v224
	v_pk_mul_f32 v[38:39], v[48:49], v[34:35]
	v_pk_fma_f32 v[34:35], v[48:49], v[34:35], v[36:37]
	v_lshlrev_b32_e32 v36, 16, v136
	v_cndmask_b32_e64 v0, v35, v39, s[0:1]
	v_cndmask_b32_e64 v34, v34, v38, s[0:1]
	v_cvt_pk_bf16_f32 v224, v34, v0
	v_lshlrev_b32_e32 v34, 16, v108
	v_and_b32_e32 v35, 0xffff0000, v108
	v_and_b32_e32 v37, 0xffff0000, v136
	v_pk_mul_f32 v[38:39], v[18:19], v[34:35]
	v_pk_fma_f32 v[18:19], v[18:19], v[34:35], v[36:37]
	v_lshlrev_b32_e32 v34, 16, v137
	v_cndmask_b32_e64 v0, v19, v39, s[0:1]
	v_cndmask_b32_e64 v18, v18, v38, s[0:1]
	v_cvt_pk_bf16_f32 v136, v18, v0
	v_lshlrev_b32_e32 v18, 16, v106
	v_and_b32_e32 v19, 0xffff0000, v106
	v_and_b32_e32 v35, 0xffff0000, v137
	v_pk_mul_f32 v[36:37], v[20:21], v[18:19]
	v_pk_fma_f32 v[18:19], v[20:21], v[18:19], v[34:35]
	v_lshlrev_b32_e32 v20, 16, v221
	v_cndmask_b32_e64 v0, v19, v37, s[0:1]
	v_cndmask_b32_e64 v18, v18, v36, s[0:1]
	v_cvt_pk_bf16_f32 v137, v18, v0
	v_lshlrev_b32_e32 v18, 16, v104
	v_and_b32_e32 v19, 0xffff0000, v104
	v_and_b32_e32 v21, 0xffff0000, v221
	v_pk_mul_f32 v[34:35], v[22:23], v[18:19]
	v_pk_fma_f32 v[18:19], v[22:23], v[18:19], v[20:21]
	v_lshlrev_b32_e32 v20, 16, v222
	v_cndmask_b32_e64 v0, v19, v35, s[0:1]
	v_cndmask_b32_e64 v18, v18, v34, s[0:1]
	v_cvt_pk_bf16_f32 v221, v18, v0
	v_lshlrev_b32_e32 v18, 16, v102
	v_and_b32_e32 v19, 0xffff0000, v102
	v_and_b32_e32 v21, 0xffff0000, v222
	v_pk_mul_f32 v[22:23], v[24:25], v[18:19]
	v_pk_fma_f32 v[18:19], v[24:25], v[18:19], v[20:21]
	v_lshlrev_b32_e32 v20, 16, v134
	v_cndmask_b32_e64 v0, v19, v23, s[0:1]
	v_cndmask_b32_e64 v18, v18, v22, s[0:1]
	v_cvt_pk_bf16_f32 v222, v18, v0
	v_lshlrev_b32_e32 v18, 16, v100
	v_and_b32_e32 v19, 0xffff0000, v100
	v_and_b32_e32 v21, 0xffff0000, v134
	v_pk_mul_f32 v[22:23], v[26:27], v[18:19]
	v_pk_fma_f32 v[18:19], v[26:27], v[18:19], v[20:21]
	v_lshlrev_b32_e32 v20, 16, v135
	v_cndmask_b32_e64 v0, v19, v23, s[0:1]
	v_cndmask_b32_e64 v18, v18, v22, s[0:1]
	v_cvt_pk_bf16_f32 v134, v18, v0
	v_lshlrev_b32_e32 v18, 16, v98
	v_and_b32_e32 v19, 0xffff0000, v98
	v_and_b32_e32 v21, 0xffff0000, v135
	v_pk_mul_f32 v[22:23], v[28:29], v[18:19]
	v_pk_fma_f32 v[18:19], v[28:29], v[18:19], v[20:21]
	v_lshlrev_b32_e32 v20, 16, v219
	v_cndmask_b32_e64 v0, v19, v23, s[0:1]
	v_cndmask_b32_e64 v18, v18, v22, s[0:1]
	v_cvt_pk_bf16_f32 v135, v18, v0
	v_lshlrev_b32_e32 v18, 16, v92
	v_and_b32_e32 v19, 0xffff0000, v92
	v_and_b32_e32 v21, 0xffff0000, v219
	v_pk_mul_f32 v[22:23], v[30:31], v[18:19]
	v_pk_fma_f32 v[18:19], v[30:31], v[18:19], v[20:21]
	v_lshlrev_b32_e32 v20, 16, v220
	v_cndmask_b32_e64 v0, v19, v23, s[0:1]
	v_cndmask_b32_e64 v18, v18, v22, s[0:1]
	v_cvt_pk_bf16_f32 v219, v18, v0
	v_lshlrev_b32_e32 v18, 16, v90
	v_and_b32_e32 v19, 0xffff0000, v90
	v_and_b32_e32 v21, 0xffff0000, v220
	v_pk_mul_f32 v[22:23], v[32:33], v[18:19]
	v_pk_fma_f32 v[18:19], v[32:33], v[18:19], v[20:21]
	v_lshlrev_b32_e32 v20, 16, v132
	v_cndmask_b32_e64 v0, v19, v23, s[0:1]
	v_cndmask_b32_e64 v18, v18, v22, s[0:1]
	v_cvt_pk_bf16_f32 v220, v18, v0
	v_lshlrev_b32_e32 v18, 16, v88
	v_and_b32_e32 v19, 0xffff0000, v88
	v_and_b32_e32 v21, 0xffff0000, v132
	v_pk_mul_f32 v[22:23], v[2:3], v[18:19]
	v_pk_fma_f32 v[2:3], v[2:3], v[18:19], v[20:21]
	v_lshlrev_b32_e32 v18, 16, v133
	v_cndmask_b32_e64 v0, v3, v23, s[0:1]
	v_cndmask_b32_e64 v2, v2, v22, s[0:1]
	v_cvt_pk_bf16_f32 v132, v2, v0
	v_lshlrev_b32_e32 v2, 16, v86
	v_and_b32_e32 v3, 0xffff0000, v86
	v_and_b32_e32 v19, 0xffff0000, v133
	v_pk_mul_f32 v[20:21], v[4:5], v[2:3]
	v_pk_fma_f32 v[2:3], v[4:5], v[2:3], v[18:19]
	v_lshlrev_b32_e32 v4, 16, v217
	v_cndmask_b32_e64 v0, v3, v21, s[0:1]
	v_cndmask_b32_e64 v2, v2, v20, s[0:1]
	v_cvt_pk_bf16_f32 v133, v2, v0
	v_lshlrev_b32_e32 v2, 16, v84
	v_and_b32_e32 v3, 0xffff0000, v84
	v_and_b32_e32 v5, 0xffff0000, v217
	v_pk_mul_f32 v[18:19], v[6:7], v[2:3]
	v_pk_fma_f32 v[2:3], v[6:7], v[2:3], v[4:5]
	v_lshlrev_b32_e32 v4, 16, v218
	v_cndmask_b32_e64 v0, v3, v19, s[0:1]
	v_cndmask_b32_e64 v2, v2, v18, s[0:1]
	v_cvt_pk_bf16_f32 v217, v2, v0
	v_lshlrev_b32_e32 v2, 16, v82
	v_and_b32_e32 v3, 0xffff0000, v82
	v_and_b32_e32 v5, 0xffff0000, v218
	v_pk_mul_f32 v[6:7], v[8:9], v[2:3]
	v_pk_fma_f32 v[2:3], v[8:9], v[2:3], v[4:5]
	v_lshlrev_b32_e32 v4, 16, v130
	v_cndmask_b32_e64 v0, v3, v7, s[0:1]
	v_cndmask_b32_e64 v2, v2, v6, s[0:1]
	v_cvt_pk_bf16_f32 v218, v2, v0
	v_lshlrev_b32_e32 v2, 16, v72
	v_and_b32_e32 v3, 0xffff0000, v72
	v_and_b32_e32 v5, 0xffff0000, v130
	v_pk_mul_f32 v[6:7], v[10:11], v[2:3]
	v_pk_fma_f32 v[2:3], v[10:11], v[2:3], v[4:5]
	v_lshlrev_b32_e32 v4, 16, v131
	v_cndmask_b32_e64 v0, v3, v7, s[0:1]
	v_cndmask_b32_e64 v2, v2, v6, s[0:1]
	v_cvt_pk_bf16_f32 v130, v2, v0
	v_lshlrev_b32_e32 v2, 16, v70
	v_and_b32_e32 v3, 0xffff0000, v70
	v_and_b32_e32 v5, 0xffff0000, v131
	v_pk_mul_f32 v[6:7], v[12:13], v[2:3]
	v_pk_fma_f32 v[2:3], v[12:13], v[2:3], v[4:5]
	v_lshlrev_b32_e32 v4, 16, v211
	v_cndmask_b32_e64 v0, v3, v7, s[0:1]
	v_cndmask_b32_e64 v2, v2, v6, s[0:1]
	v_cvt_pk_bf16_f32 v131, v2, v0
	v_lshlrev_b32_e32 v2, 16, v68
	v_and_b32_e32 v3, 0xffff0000, v68
	v_and_b32_e32 v5, 0xffff0000, v211
	v_pk_mul_f32 v[6:7], v[14:15], v[2:3]
	v_pk_fma_f32 v[2:3], v[14:15], v[2:3], v[4:5]
	v_lshlrev_b32_e32 v4, 16, v216
	v_cndmask_b32_e64 v0, v3, v7, s[0:1]
	v_cndmask_b32_e64 v2, v2, v6, s[0:1]
	v_cvt_pk_bf16_f32 v211, v2, v0
	v_lshlrev_b32_e32 v2, 16, v69
	v_and_b32_e32 v3, 0xffff0000, v69
	v_and_b32_e32 v5, 0xffff0000, v216
	v_pk_mul_f32 v[6:7], v[16:17], v[2:3]
	v_pk_fma_f32 v[2:3], v[16:17], v[2:3], v[4:5]
	s_nop 0
	v_cndmask_b32_e64 v0, v3, v7, s[0:1]
	v_cndmask_b32_e64 v2, v2, v6, s[0:1]
	v_cvt_pk_bf16_f32 v216, v2, v0
	s_cbranch_scc0 .LBB0_128

.LBB0_168:
	s_or_b64 exec, exec, s[12:13]
	v_lshlrev_b32_e32 v40, 16, v29
	v_and_b32_e32 v41, 0xffff0000, v29
	v_lshlrev_b32_e32 v42, 16, v33
	v_and_b32_e32 v43, 0xffff0000, v33
	v_pk_add_f32 v[40:41], v[40:41], v[42:43]
	v_lshlrev_b32_e32 v42, 16, v28
	v_and_b32_e32 v43, 0xffff0000, v28
	v_lshlrev_b32_e32 v28, 16, v32
	v_and_b32_e32 v29, 0xffff0000, v32
	v_pk_add_f32 v[28:29], v[42:43], v[28:29]
	v_mov_b32_e32 v32, v40
	v_mov_b32_e32 v33, v28
	v_pk_mul_f32 v[32:33], v[32:33], v[32:33]
	v_mov_b32_e32 v42, v41
	v_mov_b32_e32 v43, v29
	v_lshlrev_b32_e32 v44, 16, v12
	v_and_b32_e32 v12, 0xffff0000, v12
	v_pk_fma_f32 v[42:43], v[42:43], v[42:43], v[32:33]
	v_mul_f32_e32 v32, 0xbfb8aa3b, v44
	v_mul_f32_e32 v33, 0xbfb8aa3b, v12
	v_exp_f32_e32 v32, v32
	v_exp_f32_e32 v33, v33
	s_and_b64 s[0:1], exec, s[0:1]
	s_or_b64 s[10:11], s[0:1], s[10:11]
	v_lshl_add_u64 v[36:37], v[36:37], 0, s[8:9]
	v_pk_add_f32 v[32:33], v[32:33], 1.0 op_sel_hi:[1,0]
	v_rcp_f32_e32 v45, v33
	s_nop 0
	v_mul_f32_e32 v33, v12, v45
	v_rcp_f32_e32 v12, v32
	s_nop 0
	v_mul_f32_e32 v32, v44, v12
	v_lshlrev_b32_e32 v12, 16, v11
	v_lshlrev_b32_e32 v44, 16, v27
	v_and_b32_e32 v45, 0xffff0000, v27
	v_lshlrev_b32_e32 v46, 16, v31
	v_and_b32_e32 v47, 0xffff0000, v31
	v_and_b32_e32 v11, 0xffff0000, v11
	v_mul_f32_e32 v27, 0xbfb8aa3b, v12
	v_pk_add_f32 v[44:45], v[44:45], v[46:47]
	v_exp_f32_e32 v46, v27
	v_mul_f32_e32 v27, 0xbfb8aa3b, v11
	v_exp_f32_e32 v47, v27
	s_nop 0
	v_pk_add_f32 v[46:47], v[46:47], 1.0 op_sel_hi:[1,0]
	v_rcp_f32_e32 v27, v47
	s_nop 0
	v_mul_f32_e32 v47, v11, v27
	s_nop 1
	v_and_b32_e32 v53, 0xffff0000, v26
	v_rcp_f32_e32 v11, v46
	s_nop 0
	v_mul_f32_e32 v46, v12, v11
	v_lshlrev_b32_e32 v12, 16, v10
	v_and_b32_e32 v51, 0xffff0000, v10
	v_mul_f32_e32 v10, 0xbfb8aa3b, v12
	v_mul_f32_e32 v11, 0xbfb8aa3b, v51
	v_exp_f32_e32 v10, v10
	v_exp_f32_e32 v11, v11
	v_lshlrev_b32_e32 v52, 16, v26
	v_lshlrev_b32_e32 v26, 16, v30
	v_and_b32_e32 v27, 0xffff0000, v30
	v_pk_add_f32 v[26:27], v[52:53], v[26:27]
	v_mov_b32_e32 v31, v44
	v_mov_b32_e32 v30, v26
	v_pk_mul_f32 v[30:31], v[30:31], v[30:31]
	v_mov_b32_e32 v52, v27
	v_mov_b32_e32 v53, v45
	v_pk_add_f32 v[10:11], v[10:11], 1.0 op_sel_hi:[1,0]
	v_pk_fma_f32 v[30:31], v[52:53], v[52:53], v[30:31]
	v_rcp_f32_e32 v52, v11
	s_nop 0
	v_mul_f32_e32 v11, v51, v52
	v_rcp_f32_e32 v51, v10
	s_nop 0
	v_mul_f32_e32 v10, v12, v51
	v_add_f32_e32 v12, v30, v31
	v_add_f32_e32 v12, v43, v12
	v_add_f32_e32 v12, v42, v12
	ds_bpermute_b32 v30, v35, v12
	s_waitcnt lgkmcnt(0)
	v_add_f32_e32 v12, v12, v30
	ds_bpermute_b32 v30, v48, v12
	s_waitcnt lgkmcnt(0)
	v_add_f32_e32 v12, v12, v30
	ds_bpermute_b32 v30, v49, v12
	s_waitcnt lgkmcnt(0)
	v_add_f32_e32 v12, v12, v30
	ds_bpermute_b32 v30, v50, v12
	s_waitcnt lgkmcnt(0)
	v_add_f32_e32 v12, v12, v30
	v_fmamk_f32 v12, v12, 0x3c000000, v230
	v_cmp_gt_f32_e32 vcc, s95, v12
	v_mul_f32_e32 v30, 0x4b800000, v12
	s_nop 0
	v_cndmask_b32_e32 v12, v12, v30, vcc
	v_rsq_f32_e32 v12, v12
	s_nop 0
	v_mul_f32_e32 v30, 0x45800000, v12
	v_cndmask_b32_e32 v30, v12, v30, vcc
	v_pk_mul_f32 v[26:27], v[26:27], v[30:31] op_sel_hi:[1,0]
	s_nop 0
	v_pk_mul_f32 v[26:27], v[6:7], v[26:27]
	s_nop 0
	v_pk_mul_f32 v[10:11], v[10:11], v[26:27]
	v_pk_mul_f32 v[26:27], v[44:45], v[30:31] op_sel_hi:[1,0]
	v_cvt_pk_bf16_f32 v10, v10, v11
	v_pk_mul_f32 v[26:27], v[8:9], v[26:27]
	s_nop 0
	v_pk_mul_f32 v[26:27], v[46:47], v[26:27]
	s_nop 0
	v_cvt_pk_bf16_f32 v11, v26, v27
	v_pk_mul_f32 v[26:27], v[28:29], v[30:31] op_sel_hi:[1,0]
	v_lshlrev_b32_e32 v31, 16, v13
	v_pk_mul_f32 v[26:27], v[2:3], v[26:27]
	v_and_b32_e32 v13, 0xffff0000, v13
	v_pk_mul_f32 v[26:27], v[32:33], v[26:27]
	v_pk_mul_f32 v[28:29], v[40:41], v[30:31] op_sel_hi:[1,0]
	v_cvt_pk_bf16_f32 v12, v26, v27
	v_mul_f32_e32 v26, 0xbfb8aa3b, v31
	v_mul_f32_e32 v27, 0xbfb8aa3b, v13
	v_exp_f32_e32 v26, v26
	v_exp_f32_e32 v27, v27
	v_pk_mul_f32 v[28:29], v[4:5], v[28:29]
	v_pk_add_f32 v[26:27], v[26:27], 1.0 op_sel_hi:[1,0]
	v_rcp_f32_e32 v30, v27
	s_nop 0
	v_mul_f32_e32 v27, v13, v30
	v_rcp_f32_e32 v13, v26
	s_nop 0
	v_mul_f32_e32 v26, v31, v13
	v_pk_mul_f32 v[26:27], v[26:27], v[28:29]
	s_waitcnt vmcnt(1)
	v_mov_b64_e32 v[32:33], v[20:21]
	v_cvt_pk_bf16_f32 v13, v26, v27
	v_lshl_add_u64 v[26:27], v[38:39], 0, v[0:1]
	global_store_dwordx4 v[26:27], v[10:13], off
	v_mov_b64_e32 v[28:29], v[16:17]
	v_lshl_add_u64 v[38:39], v[38:39], 0, s[8:9]
	s_waitcnt vmcnt(0)
	v_mov_b64_e32 v[10:11], v[22:23]
	v_mov_b64_e32 v[26:27], v[14:15]
	v_mov_b64_e32 v[30:31], v[18:19]
	v_mov_b64_e32 v[12:13], v[24:25]
	s_andn2_b64 exec, exec, s[10:11]
	s_cbranch_execz .LBB0_171

.LBB0_452:
	v_and_b32_e32 v8, 0xfffffc00, v5
	v_add_u32_e32 v8, v4, v8
	v_ashrrev_i32_e32 v9, 31, v8
	v_lshl_add_u64 v[8:9], v[8:9], 2, s[20:21]
	v_cmp_gt_u32_e32 vcc, 64, v7
	v_add_u32_e32 v5, 0x2000, v5
	s_nop 0
	v_cndmask_b32_e32 v9, v9, v3, vcc
	v_cndmask_b32_e32 v8, v8, v2, vcc
	global_load_dword v8, v[8:9], off
	v_add_u32_e32 v9, 0x200, v7
	v_cmp_lt_i32_e32 vcc, 63, v7
	v_mov_b32_e32 v7, v9
	s_or_b64 s[6:7], vcc, s[6:7]
	s_waitcnt vmcnt(0)
	v_mul_f32_e32 v9, 0xbfb8aa3b, v8
	v_exp_f32_e32 v9, v9
	s_nop 0
	v_add_f32_e32 v9, 1.0, v9
	v_rcp_f32_e32 v10, v9
	s_nop 0
	v_mul_f32_e32 v8, v8, v10
	ds_write_b32 v6, v8
	v_add_u32_e32 v6, 0x800, v6
	s_andn2_b64 exec, exec, s[6:7]
	s_cbranch_execnz .LBB0_452
